# MLA: mid-tile barrier of waves 4-7 moved 16 instructions into the exp section
# speedup vs baseline: 1.0147x; 1.0147x over previous
; DI void mla_attn_phase(LAS unsigned char* lds, const bf16_t* Qg, const bf16_t* Kg, const bf16_t* Vtg, bf16_t* MIX) {
;     ...
;                     const float m_new = fmaxf(m_run, mx), alpha = __builtin_amdgcn_exp2f(m_run - m_new); m_run = m_new;
;                     float sum = 0.f;
; #pragma unroll
;                     for (int i = 0; i < 16; ++i) { s0[i] = __builtin_amdgcn_exp2f(s0[i] - m_new); s1[i] = __builtin_amdgcn_exp2f(s1[i] - m_new); sum += s0[i] + s1[i]; }
.Lmla_mid:
	v_sub_f32_e32 v80, v80, v3
	v_sub_f32_e32 v96, v96, v3
	v_exp_f32_e32 v80, v80
	v_exp_f32_e32 v96, v96
	v_sub_f32_e32 v81, v81, v3
	v_sub_f32_e32 v97, v97, v3
	v_exp_f32_e32 v81, v81
	v_exp_f32_e32 v97, v97
	v_sub_f32_e32 v82, v82, v3
	v_sub_f32_e32 v98, v98, v3
	v_exp_f32_e32 v82, v82
	v_exp_f32_e32 v98, v98
	v_sub_f32_e32 v83, v83, v3
	v_sub_f32_e32 v99, v99, v3
	v_exp_f32_e32 v83, v83
	v_exp_f32_e32 v99, v99
	s_cmp_lt_u32 s34, 0x80
	s_cbranch_scc1 .Lmla_bd1
	s_and_b64 vcc, exec, s[28:29]
	s_cbranch_vccnz .Lmla_bw1
	s_waitcnt vmcnt(4)
	s_branch .Lmla_bb1

; DI unsigned pk2(float lo, float hi) { const f32x2_t v = {lo, hi}; const bf16x2_t b = __builtin_convertvector(v, bf16x2_t); return __builtin_bit_cast(unsigned, b); }
; DI void mla_attn_phase(LAS unsigned char* lds, const bf16_t* Qg, const bf16_t* Kg, const bf16_t* Vtg, bf16_t* MIX) {
;     ...
;                     float sum = 0.f;
; #pragma unroll
;                     for (int i = 0; i < 16; ++i) { s0[i] = __builtin_amdgcn_exp2f(s0[i] - m_new); s1[i] = __builtin_amdgcn_exp2f(s1[i] - m_new); sum += s0[i] + s1[i]; }
;                     l_run = l_run * alpha + sum;
;                     if (__any(alpha != 1.f)) {
; #pragma unroll
;                         for (int mt = 0; mt < 4; ++mt)
; #pragma unroll
;                             for (int i = 0; i < 16; ++i) o[mt][i] *= alpha; }
;                     bf16x8 pf[4];
; #pragma unroll
;                     for (int sp = 0; sp < 2; ++sp) { u32x4 p0, p1;
; #pragma unroll
;                         for (int j = 0; j < 4; ++j) { p0[j] = pk2(s0[8 * sp + 2 * j], s0[8 * sp + 2 * j + 1]); p1[j] = pk2(s1[8 * sp + 2 * j], s1[8 * sp + 2 * j + 1]); }
;                         pf[sp] = __builtin_bit_cast(bf16x8, p0); pf[2 + sp] = __builtin_bit_cast(bf16x8, p1); }
;                     __builtin_amdgcn_sched_barrier(0);
;                     MLA_PV();
.Lmla_bd1:
	v_add_f32_e32 v218, v80, v96
	v_sub_f32_e32 v84, v84, v3
	v_add_f32_e32 v218, 0, v218
	v_add_f32_e32 v219, v81, v97
	v_exp_f32_e32 v226, v84
	v_sub_f32_e32 v84, v100, v3
	v_add_f32_e32 v218, v219, v218
	v_add_f32_e32 v219, v82, v98
	v_exp_f32_e32 v100, v84
	v_sub_f32_e32 v84, v85, v3
	v_add_f32_e32 v218, v219, v218
	v_add_f32_e32 v219, v83, v99
	v_exp_f32_e32 v227, v84
	v_sub_f32_e32 v84, v101, v3
	v_sub_f32_e32 v86, v86, v3
	v_exp_f32_e32 v101, v84
	v_add_f32_e32 v84, v219, v218
	v_exp_f32_e32 v218, v86
	v_sub_f32_e32 v86, v102, v3
	v_exp_f32_e32 v102, v86
	v_sub_f32_e32 v86, v87, v3
	v_exp_f32_e32 v87, v86
	v_sub_f32_e32 v86, v103, v3
	v_exp_f32_e32 v103, v86
	v_sub_f32_e32 v86, v88, v3
	v_exp_f32_e32 v88, v86
	v_sub_f32_e32 v86, v104, v3
	v_exp_f32_e32 v104, v86
	v_sub_f32_e32 v86, v89, v3
	v_exp_f32_e32 v89, v86
	v_sub_f32_e32 v86, v105, v3
	v_exp_f32_e32 v105, v86
	v_sub_f32_e32 v86, v90, v3
	v_exp_f32_e32 v90, v86
	v_sub_f32_e32 v86, v106, v3
	v_exp_f32_e32 v106, v86
	v_sub_f32_e32 v86, v91, v3
	v_exp_f32_e32 v91, v86
	v_sub_f32_e32 v86, v107, v3
	v_exp_f32_e32 v107, v86
	v_sub_f32_e32 v86, v92, v3
	v_add_f32_e32 v85, v226, v100
	v_exp_f32_e32 v219, v86
	v_sub_f32_e32 v86, v108, v3
	v_add_f32_e32 v84, v85, v84
	v_add_f32_e32 v85, v227, v101
	v_exp_f32_e32 v108, v86
	v_sub_f32_e32 v86, v93, v3
	v_add_f32_e32 v84, v85, v84
	v_add_f32_e32 v85, v218, v102
	v_exp_f32_e32 v234, v86
	v_sub_f32_e32 v86, v109, v3
	v_add_f32_e32 v84, v85, v84
	v_add_f32_e32 v85, v87, v103
	v_exp_f32_e32 v109, v86
	v_sub_f32_e32 v86, v94, v3
	v_add_f32_e32 v84, v85, v84
	v_add_f32_e32 v85, v88, v104
	v_exp_f32_e32 v235, v86
	v_sub_f32_e32 v86, v110, v3
	v_add_f32_e32 v84, v85, v84
	v_add_f32_e32 v85, v89, v105
	v_exp_f32_e32 v110, v86
	v_sub_f32_e32 v86, v95, v3
	v_add_f32_e32 v84, v85, v84
	v_add_f32_e32 v85, v90, v106
	v_exp_f32_e32 v95, v86
	v_sub_f32_e32 v86, v111, v3
	v_add_f32_e32 v84, v85, v84
	v_add_f32_e32 v85, v91, v107
	v_exp_f32_e32 v111, v86
	v_add_f32_e32 v84, v85, v84
	v_add_f32_e32 v85, v219, v108
	v_add_f32_e32 v84, v85, v84
	v_add_f32_e32 v85, v234, v109
	v_add_f32_e32 v84, v85, v84
	v_add_f32_e32 v85, v235, v110
	v_add_f32_e32 v84, v85, v84
	v_add_f32_e32 v85, v95, v111
	v_add_f32_e32 v236, v85, v84
	v_fmac_f32_e32 v236, v233, v0
	v_cvt_pk_bf16_f32 v80, v80, v81
	v_cvt_pk_bf16_f32 v84, v96, v97
	v_cvt_pk_bf16_f32 v81, v82, v83
	v_cvt_pk_bf16_f32 v85, v98, v99
	v_cvt_pk_bf16_f32 v82, v226, v227
	v_cvt_pk_bf16_f32 v86, v100, v101
	v_cvt_pk_bf16_f32 v83, v218, v87
	v_cvt_pk_bf16_f32 v87, v102, v103
	v_cvt_pk_bf16_f32 v88, v88, v89
	v_cvt_pk_bf16_f32 v92, v104, v105
	v_cvt_pk_bf16_f32 v89, v90, v91
	v_cvt_pk_bf16_f32 v93, v106, v107
	v_cvt_pk_bf16_f32 v90, v219, v234
	v_cvt_pk_bf16_f32 v94, v108, v109
	v_cvt_pk_bf16_f32 v91, v235, v95
	v_cvt_pk_bf16_f32 v95, v110, v111
	s_waitcnt lgkmcnt(6)
	v_mfma_f32_32x32x16_bf16 v[64:79], v[144:147], v[80:83], v[64:79]
	v_mfma_f32_32x32x16_bf16 v[48:63], v[140:143], v[80:83], v[48:63]
	s_waitcnt lgkmcnt(0)
	v_mfma_f32_32x32x16_bf16 v[32:47], v[148:151], v[80:83], v[32:47]
	v_mfma_f32_32x32x16_bf16 v[16:31], v[152:155], v[80:83], v[16:31]
	ds_read_b128 v[80:83], v1 offset:13376
	ds_read_b128 v[96:99], v1 offset:17984
	ds_read_b128 v[100:103], v1 offset:22592
	ds_read_b128 v[104:107], v1 offset:27200
	v_mfma_f32_32x32x16_bf16 v[64:79], v[136:139], v[88:91], v[64:79]
	v_mfma_f32_32x32x16_bf16 v[48:63], v[12:15], v[88:91], v[48:63]
	v_mfma_f32_32x32x16_bf16 v[32:47], v[4:7], v[88:91], v[32:47]
	v_mfma_f32_32x32x16_bf16 v[16:31], v[8:11], v[88:91], v[16:31]
	ds_read_b128 v[4:7], v1 offset:13408
	ds_read_b128 v[8:11], v1 offset:18016
	ds_read_b128 v[12:15], v1 offset:22624
	ds_read_b128 v[88:91], v1 offset:27232
	s_waitcnt lgkmcnt(4)
	v_mfma_f32_32x32x16_bf16 v[64:79], v[80:83], v[84:87], v[64:79]
	v_mov_b32_e32 v233, v236
	v_mfma_f32_32x32x16_bf16 v[48:63], v[96:99], v[84:87], v[48:63]
	v_mfma_f32_32x32x16_bf16 v[32:47], v[100:103], v[84:87], v[32:47]
	v_mfma_f32_32x32x16_bf16 v[16:31], v[104:107], v[84:87], v[16:31]
	s_waitcnt lgkmcnt(0)
	v_mfma_f32_32x32x16_bf16 v[64:79], v[4:7], v[92:95], v[64:79]
	v_mfma_f32_32x32x16_bf16 v[48:63], v[8:11], v[92:95], v[48:63]
	v_mfma_f32_32x32x16_bf16 v[32:47], v[12:15], v[92:95], v[32:47]
	v_mfma_f32_32x32x16_bf16 v[16:31], v[88:91], v[92:95], v[16:31]
	s_branch .Lmla_tail
